# attention modes 0 and 1: softmax exp/add/pack stream re-spread over the MFMA gaps (exps front-loaded into the first ~80 percent of gaps, light tile tail), single row-sum accumulator
# speedup vs baseline: 1.0187x; 1.0020x over previous
.LBB0_959:
	s_add_i32 s41, s41, 2
	s_cmp_gt_u32 s41, 1
	s_cselect_b32 s30, s40, s62
	s_mulk_i32 s30, 0x5000
	v_add_u32_e32 v142, s30, v197
	v_add_u32_e32 v158, 0xc800, v142
	s_waitcnt lgkmcnt(6)
	v_mfma_f32_32x32x16_bf16 v[18:33], v[106:109], v[138:141], v[18:33]
	ds_read_b64_tr_b16 v[110:111], v142 offset:61440
	ds_read_b64_tr_b16 v[112:113], v142 offset:64000
	s_mul_i32 s63, s39, 0x5000
	s_add_i32 s30, s63, 0
	v_mov_b32_e32 v250, 0
	v_exp_f32_e32 v66, v66
	v_exp_f32_e32 v67, v67
	v_add_f32_e32 v250, v66, v250
	v_add_f32_e32 v250, v67, v250
	v_cvt_pk_bf16_f32 v66, v66, v67
	s_waitcnt lgkmcnt(6)
	v_mfma_f32_32x32x16_bf16 v[2:17], v[102:105], v[138:141], v[2:17]
	ds_read_b64_tr_b16 v[106:107], v142 offset:61504
	ds_read_b64_tr_b16 v[108:109], v142 offset:64064
	v_lshl_add_u64 v[102:103], s[4:5], 0, v[186:187]
	global_load_dwordx4 v[154:157], v[102:103], off
	v_lshl_add_u64 v[102:103], s[4:5], 0, v[184:185]
	global_load_dwordx4 v[146:149], v[102:103], off
	v_lshl_add_u64 v[102:103], s[4:5], 0, v[182:183]
	global_load_dwordx4 v[150:153], v[102:103], off
	v_lshl_add_u64 v[192:193], s[0:1], 0, v[180:181]
	s_mov_b32 s65, 0x10000
	v_add_co_u32_e32 v102, vcc, s65, v192
	v_lshl_add_u64 v[194:195], s[0:1], 0, v[178:179]
	s_nop 0
	v_addc_co_u32_e32 v103, vcc, 0, v193, vcc
	v_add_co_u32_e32 v104, vcc, s65, v194
	v_exp_f32_e32 v68, v68
	v_exp_f32_e32 v69, v69
	v_add_f32_e32 v250, v68, v250
	v_add_f32_e32 v250, v69, v250
	v_cvt_pk_bf16_f32 v67, v68, v69
	s_waitcnt lgkmcnt(6)
	v_mfma_f32_32x32x16_bf16 v[18:33], v[94:97], v[98:101], v[18:33]
	v_addc_co_u32_e32 v105, vcc, 0, v195, vcc
	global_load_dwordx4 v[138:141], v[102:103], off
	global_load_dwordx4 v[142:145], v[104:105], off
	ds_read_b64_tr_b16 v[102:103], v158 offset:15360
	ds_read_b64_tr_b16 v[104:105], v158 offset:17920
	v_exp_f32_e32 v70, v70
	v_exp_f32_e32 v71, v71
	v_add_f32_e32 v250, v70, v250
	v_add_f32_e32 v250, v71, v250
	v_cvt_pk_bf16_f32 v68, v70, v71
	s_waitcnt lgkmcnt(6)
	v_mfma_f32_32x32x16_bf16 v[2:17], v[90:93], v[98:101], v[2:17]
	ds_read_b64_tr_b16 v[94:95], v158 offset:15424
	ds_read_b64_tr_b16 v[96:97], v158 offset:17984
	v_exp_f32_e32 v72, v72
	s_waitcnt lgkmcnt(6)
	v_mfma_f32_32x32x16_bf16 v[18:33], v[110:113], v[82:85], v[18:33]
	ds_read_b128 v[90:93], v206
	v_add_f32_e32 v250, v72, v250
	v_exp_f32_e32 v73, v73
	v_exp_f32_e32 v74, v74
	v_add_f32_e32 v250, v73, v250
	v_add_f32_e32 v250, v74, v250
	v_cvt_pk_bf16_f32 v69, v72, v73
	s_waitcnt lgkmcnt(5)
	v_mfma_f32_32x32x16_bf16 v[2:17], v[106:109], v[82:85], v[2:17]
	ds_read_b128 v[158:161], v206 offset:12800
	v_exp_f32_e32 v75, v75
	v_exp_f32_e32 v76, v76
	v_add_f32_e32 v250, v75, v250
	v_add_f32_e32 v250, v76, v250
	v_cvt_pk_bf16_f32 v70, v74, v75
	s_waitcnt lgkmcnt(4)
	v_mfma_f32_32x32x16_bf16 v[18:33], v[102:105], v[86:89], v[18:33]
	ds_read_b128 v[162:165], v206 offset:32
	v_exp_f32_e32 v77, v77
	v_exp_f32_e32 v78, v78
	v_add_f32_e32 v250, v77, v250
	v_add_f32_e32 v250, v78, v250
	v_cvt_pk_bf16_f32 v71, v76, v77
	s_waitcnt lgkmcnt(3)
	v_mfma_f32_32x32x16_bf16 v[2:17], v[94:97], v[86:89], v[2:17]
	ds_read_b128 v[220:223], v206 offset:12832
	v_exp_f32_e32 v79, v79
	s_waitcnt lgkmcnt(3)
	v_mfma_f32_32x32x16_bf16 v[98:113], v[90:93], v[114:117], v[50:65]
	ds_read_b128 v[224:227], v206 offset:64
	v_add_f32_e32 v250, v79, v250
	v_exp_f32_e32 v80, v80
	v_exp_f32_e32 v81, v81
	v_add_f32_e32 v250, v80, v250
	v_add_f32_e32 v250, v81, v250
	v_cvt_pk_bf16_f32 v72, v78, v79
	v_cvt_pk_bf16_f32 v73, v80, v81
	s_waitcnt lgkmcnt(3)
	v_mfma_f32_32x32x16_bf16 v[82:97], v[158:161], v[114:117], v[50:65]
	ds_read_b128 v[76:79], v206 offset:12864
	v_exp_f32_e32 v34, v34
	v_exp_f32_e32 v35, v35
	v_add_f32_e32 v250, v34, v250
	v_add_f32_e32 v250, v35, v250
	v_cvt_pk_bf16_f32 v74, v34, v35
	s_waitcnt lgkmcnt(3)
	v_mfma_f32_32x32x16_bf16 v[98:113], v[162:165], v[118:121], v[98:113]
	ds_read_b128 v[158:161], v206 offset:96
	v_exp_f32_e32 v36, v36
	v_exp_f32_e32 v37, v37
	v_add_f32_e32 v250, v36, v250
	v_add_f32_e32 v250, v37, v250
	v_cvt_pk_bf16_f32 v75, v36, v37
	s_waitcnt lgkmcnt(3)
	v_mfma_f32_32x32x16_bf16 v[82:97], v[220:223], v[118:121], v[82:97]
	ds_read_b128 v[162:165], v206 offset:12896
	v_exp_f32_e32 v38, v38
	s_waitcnt lgkmcnt(3)
	v_mfma_f32_32x32x16_bf16 v[98:113], v[224:227], v[122:125], v[98:113]
	ds_read_b128 v[220:223], v206 offset:128
	v_add_f32_e32 v250, v38, v250
	v_exp_f32_e32 v39, v39
	v_exp_f32_e32 v40, v40
	v_add_f32_e32 v250, v39, v250
	v_add_f32_e32 v250, v40, v250
	s_waitcnt lgkmcnt(3)
	v_mfma_f32_32x32x16_bf16 v[82:97], v[76:79], v[122:125], v[82:97]
	ds_read_b128 v[34:37], v206 offset:12928
	v_exp_f32_e32 v41, v41
	v_exp_f32_e32 v42, v42
	v_add_f32_e32 v250, v41, v250
	v_add_f32_e32 v250, v42, v250
	s_waitcnt lgkmcnt(3)
	v_mfma_f32_32x32x16_bf16 v[98:113], v[158:161], v[126:129], v[98:113]
	ds_read_b128 v[224:227], v206 offset:160
	v_exp_f32_e32 v43, v43
	v_exp_f32_e32 v44, v44
	v_add_f32_e32 v250, v43, v250
	v_add_f32_e32 v250, v44, v250
	v_cvt_pk_bf16_f32 v76, v38, v39
	v_cvt_pk_bf16_f32 v77, v40, v41
	s_waitcnt lgkmcnt(3)
	v_mfma_f32_32x32x16_bf16 v[82:97], v[162:165], v[126:129], v[82:97]
	ds_read_b128 v[38:41], v206 offset:12960
	v_exp_f32_e32 v45, v45
	v_cvt_pk_bf16_f32 v78, v42, v43
	v_add_f32_e32 v250, v45, v250
	s_waitcnt lgkmcnt(3)
	v_mfma_f32_32x32x16_bf16 v[98:113], v[220:223], v[130:133], v[98:113]
	s_waitcnt vmcnt(4)
	ds_write_b128 v202, v[154:157] offset:25600
	s_waitcnt vmcnt(3)
	ds_write_b128 v200, v[146:149] offset:25600
	s_waitcnt vmcnt(2)
	ds_write_b128 v201, v[150:153] offset:25600
	v_exp_f32_e32 v46, v46
	v_exp_f32_e32 v47, v47
	v_add_f32_e32 v250, v46, v250
	v_add_f32_e32 v250, v47, v250
	v_cvt_pk_bf16_f32 v79, v44, v45
	s_waitcnt lgkmcnt(5)
	v_mfma_f32_32x32x16_bf16 v[82:97], v[34:37], v[130:133], v[82:97]
	v_exp_f32_e32 v48, v48
	v_exp_f32_e32 v49, v49
	v_add_f32_e32 v250, v48, v250
	v_add_f32_e32 v250, v49, v250
	v_cvt_pk_bf16_f32 v80, v46, v47
	s_waitcnt lgkmcnt(4)
	v_mfma_f32_32x32x16_bf16 v[98:113], v[224:227], v[134:137], v[98:113]
	v_add_u32_e32 v36, s30, v204
	s_waitcnt vmcnt(1)
	ds_write_b128 v36, v[138:141] offset:51200
	v_add_u32_e32 v36, s30, v205
	s_waitcnt vmcnt(0)
	ds_write_b128 v36, v[142:145] offset:51200
	v_cvt_pk_bf16_f32 v81, v48, v49
	s_waitcnt lgkmcnt(5)
	v_mfma_f32_32x32x16_bf16 v[82:97], v[38:41], v[134:137], v[82:97]
	v_mov_b32_e32 v209, v250
	s_mul_i32 s30, s62, 0x5000
	v_add_u32_e32 v138, s30, v197
	ds_read_b64_tr_b16 v[148:149], v138 offset:51200
	ds_read_b64_tr_b16 v[150:151], v138 offset:53760
	ds_read_b64_tr_b16 v[146:147], v138 offset:53824
	ds_read_b64_tr_b16 v[144:145], v138 offset:51264
	ds_read_b64_tr_b16 v[152:153], v138 offset:56320
	ds_read_b64_tr_b16 v[154:155], v138 offset:58880
	ds_read_b64_tr_b16 v[142:143], v138 offset:58944
	ds_read_b64_tr_b16 v[140:141], v138 offset:56384
	v_cmp_lt_f32_e32 vcc, s66, v209
	s_cbranch_vccz .LBB0_961
	v_log_f32_e32 v34, v209
	s_nop 0
	v_floor_f32_e32 v34, v34
	v_cndmask_b32_e32 v34, 0, v34, vcc
	v_mov_b32_e32 v35, v34
	s_nop 1
	v_permlane32_swap_b32_e32 v34, v35
	v_max_f32_e32 v35, v35, v35
	v_max_f32_e32 v34, v34, v34
	v_max_f32_e32 v35, v34, v35
	v_exp_f32_e64 v190, -v35
	v_add_f32_e32 v207, v207, v35
	v_sub_f32_e32 v34, 0, v207
	v_sub_f32_e32 v113, v113, v35
	v_sub_f32_e32 v112, v112, v35
	v_sub_f32_e32 v111, v111, v35
	v_sub_f32_e32 v110, v110, v35
	v_sub_f32_e32 v109, v109, v35
	v_sub_f32_e32 v108, v108, v35
	v_sub_f32_e32 v107, v107, v35
	v_sub_f32_e32 v106, v106, v35
	v_sub_f32_e32 v105, v105, v35
	v_sub_f32_e32 v104, v104, v35
	v_sub_f32_e32 v103, v103, v35
	v_sub_f32_e32 v102, v102, v35
	v_sub_f32_e32 v101, v101, v35
	v_sub_f32_e32 v100, v100, v35
	v_sub_f32_e32 v99, v99, v35
	v_sub_f32_e32 v98, v98, v35
	v_sub_f32_e32 v97, v97, v35
	v_sub_f32_e32 v96, v96, v35
	v_sub_f32_e32 v95, v95, v35
	v_sub_f32_e32 v94, v94, v35
	v_sub_f32_e32 v93, v93, v35
	v_sub_f32_e32 v92, v92, v35
	v_sub_f32_e32 v91, v91, v35
	v_sub_f32_e32 v90, v90, v35
	v_sub_f32_e32 v89, v89, v35
	v_sub_f32_e32 v88, v88, v35
	v_sub_f32_e32 v87, v87, v35
	v_sub_f32_e32 v86, v86, v35
	v_sub_f32_e32 v85, v85, v35
	v_sub_f32_e32 v84, v84, v35
	v_sub_f32_e32 v83, v83, v35
	v_sub_f32_e32 v82, v82, v35
	v_mov_b32_e32 v35, v34
	v_mov_b32_e32 v36, v34
	v_mov_b32_e32 v37, v34
	v_mov_b32_e32 v38, v34
	v_mov_b32_e32 v39, v34
	v_mov_b32_e32 v40, v34
	v_mov_b32_e32 v41, v34
	v_mov_b32_e32 v42, v34
	v_mov_b32_e32 v43, v34
	v_mov_b32_e32 v44, v34
	v_mov_b32_e32 v45, v34
	v_mov_b32_e32 v46, v34
	v_mov_b32_e32 v47, v34
	v_mov_b32_e32 v48, v34
	v_mov_b32_e32 v49, v34
	v_mov_b32_e32 v50, v34
	v_mov_b32_e32 v51, v34
	v_mov_b32_e32 v52, v34
	v_mov_b32_e32 v53, v34
	v_mov_b32_e32 v54, v34
	v_mov_b32_e32 v55, v34
	v_mov_b32_e32 v56, v34
	v_mov_b32_e32 v57, v34
	v_mov_b32_e32 v58, v34
	v_mov_b32_e32 v59, v34
	v_mov_b32_e32 v60, v34
	v_mov_b32_e32 v61, v34
	v_mov_b32_e32 v62, v34
	v_mov_b32_e32 v63, v34
	v_mov_b32_e32 v64, v34
	v_mov_b32_e32 v65, v34
	s_branch .LBB0_962

.LBB0_964:
	v_add_u32_e32 v139, 0xc800, v138
	s_nop 0
	v_mfma_f32_32x32x16_bf16 v[18:33], v[148:151], v[66:69], v[18:33]
	ds_read_b64_tr_b16 v[220:221], v138 offset:61440
	ds_read_b64_tr_b16 v[222:223], v138 offset:64000
	s_min_u32 s30, s41, 0x7e
	s_lshl_b32 s30, s30, 6
	s_add_i32 s30, s38, s30
	s_mulk_i32 s30, 0x180
	s_lshl_b64 s[70:71], s[30:31], 1
	s_add_u32 s70, s26, s70
	s_mul_i32 s30, s40, 0x5000
	s_addc_u32 s71, s27, s71
	s_add_i32 s30, s30, 0
	v_mov_b32_e32 v250, 0
	v_exp_f32_e32 v98, v98
	v_exp_f32_e32 v99, v99
	v_add_f32_e32 v250, v98, v250
	v_add_f32_e32 v250, v99, v250
	v_mfma_f32_32x32x16_bf16 v[2:17], v[144:147], v[66:69], v[2:17]
	ds_read_b64_tr_b16 v[224:225], v138 offset:61504
	ds_read_b64_tr_b16 v[226:227], v138 offset:64064
	v_lshl_add_u64 v[66:67], v[168:169], 1, s[70:71]
	global_load_dwordx4 v[164:167], v[66:67], off
	v_lshl_add_u64 v[66:67], v[174:175], 1, s[70:71]
	global_load_dwordx4 v[156:159], v[66:67], off
	v_lshl_add_u64 v[66:67], v[176:177], 1, s[70:71]
	global_load_dwordx4 v[160:163], v[66:67], off
	s_mov_b32 s65, 0x18000
	v_add_co_u32_e32 v66, vcc, s65, v192
	v_exp_f32_e32 v228, v100
	v_exp_f32_e32 v229, v101
	v_add_f32_e32 v250, v228, v250
	v_add_f32_e32 v250, v229, v250
	v_mfma_f32_32x32x16_bf16 v[18:33], v[152:155], v[70:73], v[18:33]
	s_nop 0
	v_addc_co_u32_e32 v67, vcc, 0, v193, vcc
	v_add_co_u32_e32 v68, vcc, s65, v194
	v_addc_co_u32_e32 v69, vcc, 0, v195, vcc
	global_load_dwordx4 v[144:147], v[66:67], off
	global_load_dwordx4 v[148:151], v[68:69], off
	ds_read_b64_tr_b16 v[66:67], v139 offset:15360
	ds_read_b64_tr_b16 v[68:69], v139 offset:17920
	v_exp_f32_e32 v102, v102
	v_exp_f32_e32 v103, v103
	v_add_f32_e32 v250, v102, v250
	v_add_f32_e32 v250, v103, v250
	v_cvt_pk_bf16_f32 v138, v98, v99
	v_mfma_f32_32x32x16_bf16 v[2:17], v[140:143], v[70:73], v[2:17]
	ds_read_b64_tr_b16 v[98:99], v139 offset:15424
	ds_read_b64_tr_b16 v[100:101], v139 offset:17984
	v_exp_f32_e32 v104, v104
	s_waitcnt lgkmcnt(6)
	v_mfma_f32_32x32x16_bf16 v[18:33], v[220:223], v[74:77], v[18:33]
	ds_read_b128 v[152:155], v206 offset:25600
	v_add_f32_e32 v250, v104, v250
	v_exp_f32_e32 v105, v105
	v_exp_f32_e32 v230, v106
	v_add_f32_e32 v250, v105, v250
	v_add_f32_e32 v250, v230, v250
	v_cvt_pk_bf16_f32 v139, v228, v229
	s_waitcnt lgkmcnt(5)
	v_mfma_f32_32x32x16_bf16 v[2:17], v[224:227], v[74:77], v[2:17]
	ds_read_b128 v[192:195], v206 offset:38400
	v_exp_f32_e32 v231, v107
	v_exp_f32_e32 v232, v108
	v_add_f32_e32 v250, v231, v250
	v_add_f32_e32 v250, v232, v250
	v_cvt_pk_bf16_f32 v140, v102, v103
	v_cvt_pk_bf16_f32 v141, v104, v105
	s_waitcnt lgkmcnt(4)
	v_mfma_f32_32x32x16_bf16 v[18:33], v[66:69], v[78:81], v[18:33]
	ds_read_b128 v[102:105], v206 offset:25632
	v_exp_f32_e32 v233, v109
	v_exp_f32_e32 v110, v110
	v_add_f32_e32 v250, v233, v250
	v_add_f32_e32 v250, v110, v250
	s_waitcnt lgkmcnt(3)
	v_mfma_f32_32x32x16_bf16 v[2:17], v[98:101], v[78:81], v[2:17]
	ds_read_b128 v[220:223], v206 offset:38432
	ds_read_b128 v[106:109], v206 offset:25664
	v_exp_f32_e32 v111, v111
	s_waitcnt lgkmcnt(4)
	v_mfma_f32_32x32x16_bf16 v[66:81], v[152:155], v[114:117], v[34:49]
	v_add_f32_e32 v250, v111, v250
	v_exp_f32_e32 v112, v112
	v_exp_f32_e32 v113, v113
	v_add_f32_e32 v250, v112, v250
	v_add_f32_e32 v250, v113, v250
	v_cvt_pk_bf16_f32 v98, v230, v231
	s_waitcnt lgkmcnt(3)
	v_mfma_f32_32x32x16_bf16 v[34:49], v[192:195], v[114:117], v[34:49]
	ds_read_b128 v[152:155], v206 offset:38464
	v_exp_f32_e32 v82, v82
	v_exp_f32_e32 v83, v83
	v_add_f32_e32 v250, v82, v250
	v_add_f32_e32 v250, v83, v250
	v_cvt_pk_bf16_f32 v99, v232, v233
	v_cvt_pk_bf16_f32 v100, v110, v111
	v_cvt_pk_bf16_f32 v101, v112, v113
	s_waitcnt lgkmcnt(3)
	v_mfma_f32_32x32x16_bf16 v[66:81], v[102:105], v[118:121], v[66:81]
	ds_read_b128 v[110:113], v206 offset:25696
	v_exp_f32_e32 v84, v84
	v_exp_f32_e32 v85, v85
	v_add_f32_e32 v250, v84, v250
	v_add_f32_e32 v250, v85, v250
	v_cvt_pk_bf16_f32 v82, v82, v83
	s_waitcnt lgkmcnt(3)
	v_mfma_f32_32x32x16_bf16 v[34:49], v[220:223], v[118:121], v[34:49]
	ds_read_b128 v[102:105], v206 offset:38496
	v_exp_f32_e32 v86, v86
	v_cvt_pk_bf16_f32 v83, v84, v85
	v_add_f32_e32 v250, v86, v250
	s_waitcnt lgkmcnt(3)
	v_mfma_f32_32x32x16_bf16 v[66:81], v[106:109], v[122:125], v[66:81]
	ds_read_b128 v[192:195], v206 offset:25728
	v_exp_f32_e32 v87, v87
	v_exp_f32_e32 v88, v88
	v_add_f32_e32 v250, v87, v250
	v_add_f32_e32 v250, v88, v250
	v_cvt_pk_bf16_f32 v84, v86, v87
	s_waitcnt lgkmcnt(3)
	v_mfma_f32_32x32x16_bf16 v[34:49], v[152:155], v[122:125], v[34:49]
	ds_read_b128 v[106:109], v206 offset:38528
	v_exp_f32_e32 v89, v89
	v_exp_f32_e32 v90, v90
	v_add_f32_e32 v250, v89, v250
	v_add_f32_e32 v250, v90, v250
	v_cvt_pk_bf16_f32 v85, v88, v89
	s_waitcnt lgkmcnt(3)
	v_mfma_f32_32x32x16_bf16 v[66:81], v[110:113], v[126:129], v[66:81]
	ds_read_b128 v[152:155], v206 offset:25760
	v_exp_f32_e32 v91, v91
	v_exp_f32_e32 v92, v92
	v_add_f32_e32 v250, v91, v250
	v_add_f32_e32 v250, v92, v250
	v_cvt_pk_bf16_f32 v86, v90, v91
	s_waitcnt lgkmcnt(3)
	v_mfma_f32_32x32x16_bf16 v[34:49], v[102:105], v[126:129], v[34:49]
	ds_read_b128 v[110:113], v206 offset:38560
	v_exp_f32_e32 v93, v93
	s_waitcnt lgkmcnt(3)
	v_mfma_f32_32x32x16_bf16 v[66:81], v[192:195], v[130:133], v[66:81]
	s_waitcnt vmcnt(4)
	ds_write_b128 v202, v[164:167]
	s_waitcnt vmcnt(3)
	ds_write_b128 v200, v[156:159]
	s_waitcnt vmcnt(2)
	ds_write_b128 v201, v[160:163]
	v_add_f32_e32 v250, v93, v250
	v_exp_f32_e32 v94, v94
	v_exp_f32_e32 v95, v95
	v_add_f32_e32 v250, v94, v250
	v_add_f32_e32 v250, v95, v250
	v_cvt_pk_bf16_f32 v87, v92, v93
	v_cvt_pk_bf16_f32 v88, v94, v95
	s_waitcnt lgkmcnt(5)
	v_mfma_f32_32x32x16_bf16 v[34:49], v[106:109], v[130:133], v[34:49]
	v_exp_f32_e32 v96, v96
	v_exp_f32_e32 v97, v97
	v_add_f32_e32 v250, v96, v250
	v_add_f32_e32 v250, v97, v250
	v_cvt_pk_bf16_f32 v89, v96, v97
	s_waitcnt lgkmcnt(4)
	v_mfma_f32_32x32x16_bf16 v[66:81], v[152:155], v[134:137], v[66:81]
	v_add_u32_e32 v91, s30, v204
	s_waitcnt vmcnt(1)
	ds_write_b128 v91, v[144:147] offset:51200
	v_add_u32_e32 v91, s30, v205
	s_waitcnt vmcnt(0)
	ds_write_b128 v91, v[148:151] offset:51200
	s_waitcnt lgkmcnt(5)
	v_mfma_f32_32x32x16_bf16 v[34:49], v[110:113], v[134:137], v[34:49]
	v_mov_b32_e32 v143, v250
	v_add_u32_e32 v90, s63, v197
	ds_read_b64_tr_b16 v[106:107], v90 offset:51200
	ds_read_b64_tr_b16 v[108:109], v90 offset:53760
	ds_read_b64_tr_b16 v[104:105], v90 offset:53824
	ds_read_b64_tr_b16 v[102:103], v90 offset:51264
	ds_read_b64_tr_b16 v[94:95], v90 offset:56320
	ds_read_b64_tr_b16 v[96:97], v90 offset:58880
	ds_read_b64_tr_b16 v[92:93], v90 offset:58944
	ds_read_b64_tr_b16 v[90:91], v90 offset:56384
	v_cmp_lt_f32_e32 vcc, s66, v143
	s_cbranch_vccz .LBB0_966
	v_log_f32_e32 v50, v143
	s_nop 0
	v_floor_f32_e32 v50, v50
	v_cndmask_b32_e32 v50, 0, v50, vcc
	v_mov_b32_e32 v51, v50
	s_nop 1
	v_permlane32_swap_b32_e32 v50, v51
	v_max_f32_e32 v51, v51, v51
	v_max_f32_e32 v50, v50, v50
	v_max_f32_e32 v51, v50, v51
	v_exp_f32_e64 v142, -v51
	v_add_f32_e32 v207, v207, v51
	v_sub_f32_e32 v50, 0, v207
	v_sub_f32_e32 v81, v81, v51
	v_sub_f32_e32 v80, v80, v51
	v_sub_f32_e32 v79, v79, v51
	v_sub_f32_e32 v78, v78, v51
	v_sub_f32_e32 v77, v77, v51
	v_sub_f32_e32 v76, v76, v51
	v_sub_f32_e32 v75, v75, v51
	v_sub_f32_e32 v74, v74, v51
	v_sub_f32_e32 v73, v73, v51
	v_sub_f32_e32 v72, v72, v51
	v_sub_f32_e32 v71, v71, v51
	v_sub_f32_e32 v70, v70, v51
	v_sub_f32_e32 v69, v69, v51
	v_sub_f32_e32 v68, v68, v51
	v_sub_f32_e32 v67, v67, v51
	v_sub_f32_e32 v66, v66, v51
	v_sub_f32_e32 v49, v49, v51
	v_sub_f32_e32 v48, v48, v51
	v_sub_f32_e32 v47, v47, v51
	v_sub_f32_e32 v46, v46, v51
	v_sub_f32_e32 v45, v45, v51
	v_sub_f32_e32 v44, v44, v51
	v_sub_f32_e32 v43, v43, v51
	v_sub_f32_e32 v42, v42, v51
	v_sub_f32_e32 v41, v41, v51
	v_sub_f32_e32 v40, v40, v51
	v_sub_f32_e32 v39, v39, v51
	v_sub_f32_e32 v38, v38, v51
	v_sub_f32_e32 v37, v37, v51
	v_sub_f32_e32 v36, v36, v51
	v_sub_f32_e32 v35, v35, v51
	v_sub_f32_e32 v34, v34, v51
	v_mov_b32_e32 v51, v50
	v_mov_b32_e32 v52, v50
	v_mov_b32_e32 v53, v50
	v_mov_b32_e32 v54, v50
	v_mov_b32_e32 v55, v50
	v_mov_b32_e32 v56, v50
	v_mov_b32_e32 v57, v50
	v_mov_b32_e32 v58, v50
	v_mov_b32_e32 v59, v50
	v_mov_b32_e32 v60, v50
	v_mov_b32_e32 v61, v50
	v_mov_b32_e32 v62, v50
	v_mov_b32_e32 v63, v50
	v_mov_b32_e32 v64, v50
	v_mov_b32_e32 v65, v50
	s_branch .LBB0_967

.LBB0_985:
	s_waitcnt lgkmcnt(3)
	v_mfma_f32_32x32x16_bf16 v[50:65], v[158:161], v[142:145], v[50:65]
	s_add_i32 s52, s73, s75
	s_add_i32 s0, s75, 0xffffff80
	s_add_i32 s37, s52, 0xffffff80
	s_cmp_lt_i32 s0, s70
	s_cselect_b64 s[6:7], -1, 0
	s_sub_i32 s0, s52, 64
	s_cmpk_gt_i32 s0, 0xff66
	s_cselect_b64 s[0:1], -1, 0
	s_add_i32 s36, s52, 0xffffffa1
	s_cmpk_gt_i32 s36, 0x5a
	s_cselect_b64 s[4:5], -1, 0
	s_cmp_gt_u32 s76, 1
	s_cselect_b32 s53, s74, s77
	s_mulk_i32 s53, 0x5000
	s_cmpk_gt_i32 s37, 0xff66
	v_add_u32_e32 v180, s53, v192
	s_cselect_b64 s[78:79], -1, 0
	v_add_u32_e32 v199, 0xc800, v180
	s_and_b64 s[6:7], s[78:79], s[6:7]
	ds_read_b64_tr_b16 v[200:201], v180 offset:56320
	ds_read_b64_tr_b16 v[202:203], v180 offset:58880
	s_mul_i32 s78, s72, 0x5000
	s_add_i32 s37, s78, 0
	v_mov_b32_e32 v224, 0
	v_exp_f32_e32 v98, v98
	v_exp_f32_e32 v99, v99
	v_add_f32_e32 v224, v98, v224
	v_add_f32_e32 v224, v99, v224
	s_waitcnt lgkmcnt(4)
	v_mfma_f32_32x32x16_bf16 v[34:49], v[154:157], v[142:145], v[34:49]
	ds_read_b64_tr_b16 v[204:205], v180 offset:56384
	ds_read_b64_tr_b16 v[206:207], v180 offset:58944
	global_load_dwordx4 v[162:165], v168, s[84:85] offset:1024
	global_load_dwordx4 v[158:161], v170, s[84:85] offset:1024
	v_exp_f32_e32 v100, v100
	s_waitcnt lgkmcnt(5)
	v_mfma_f32_32x32x16_bf16 v[18:33], v[150:153], v[142:145], v[18:33]
	ds_read_b64_tr_b16 v[208:209], v180 offset:56448
	ds_read_b64_tr_b16 v[210:211], v180 offset:59008
	global_load_dwordx4 v[150:153], v168, s[98:99] offset:2048
	global_load_dwordx4 v[154:157], v170, s[98:99] offset:2048
	v_add_f32_e32 v224, v100, v224
	v_exp_f32_e32 v101, v101
	v_exp_f32_e32 v102, v102
	v_add_f32_e32 v224, v101, v224
	v_add_f32_e32 v224, v102, v224
	s_waitcnt lgkmcnt(6)
	v_mfma_f32_32x32x16_bf16 v[2:17], v[146:149], v[142:145], v[2:17]
	ds_read_b64_tr_b16 v[220:221], v180 offset:56512
	ds_read_b64_tr_b16 v[222:223], v180 offset:59072
	v_exp_f32_e32 v103, v103
	s_waitcnt lgkmcnt(6)
	v_mfma_f32_32x32x16_bf16 v[50:65], v[200:203], v[138:141], v[50:65]
	ds_read_b64_tr_b16 v[146:147], v180 offset:61440
	ds_read_b64_tr_b16 v[148:149], v180 offset:64000
	v_add_f32_e32 v224, v103, v224
	v_exp_f32_e32 v104, v104
	v_exp_f32_e32 v105, v105
	v_add_f32_e32 v224, v104, v224
	v_add_f32_e32 v224, v105, v224
	v_cvt_pk_bf16_f32 v142, v98, v99
	s_waitcnt lgkmcnt(6)
	v_mfma_f32_32x32x16_bf16 v[34:49], v[204:207], v[138:141], v[34:49]
	ds_read_b64_tr_b16 v[200:201], v180 offset:61504
	ds_read_b64_tr_b16 v[202:203], v180 offset:64064
	v_exp_f32_e32 v106, v106
	v_exp_f32_e32 v107, v107
	v_add_f32_e32 v224, v106, v224
	v_add_f32_e32 v224, v107, v224
	v_cvt_pk_bf16_f32 v143, v100, v101
	s_waitcnt lgkmcnt(6)
	v_mfma_f32_32x32x16_bf16 v[18:33], v[208:211], v[138:141], v[18:33]
	ds_read_b64_tr_b16 v[98:99], v180 offset:61568
	ds_read_b64_tr_b16 v[100:101], v180 offset:64128
	v_exp_f32_e32 v108, v108
	v_cvt_pk_bf16_f32 v144, v102, v103
	v_add_f32_e32 v224, v108, v224
	s_waitcnt lgkmcnt(6)
	v_mfma_f32_32x32x16_bf16 v[2:17], v[220:223], v[138:141], v[2:17]
	ds_read_b64_tr_b16 v[204:205], v180 offset:61632
	ds_read_b64_tr_b16 v[206:207], v180 offset:64192
	v_exp_f32_e32 v109, v109
	v_exp_f32_e32 v110, v110
	v_add_f32_e32 v224, v109, v224
	v_add_f32_e32 v224, v110, v224
	s_waitcnt lgkmcnt(6)
	v_mfma_f32_32x32x16_bf16 v[50:65], v[146:149], v[134:137], v[50:65]
	ds_read_b64_tr_b16 v[208:209], v199 offset:15360
	ds_read_b64_tr_b16 v[210:211], v199 offset:17920
	v_exp_f32_e32 v111, v111
	v_cvt_pk_bf16_f32 v145, v104, v105
	v_add_f32_e32 v224, v111, v224
	v_cvt_pk_bf16_f32 v140, v110, v111
	s_waitcnt lgkmcnt(6)
	v_mfma_f32_32x32x16_bf16 v[34:49], v[200:203], v[134:137], v[34:49]
	ds_read_b64_tr_b16 v[102:103], v199 offset:15424
	ds_read_b64_tr_b16 v[104:105], v199 offset:17984
	v_exp_f32_e32 v112, v112
	v_exp_f32_e32 v113, v113
	v_add_f32_e32 v224, v112, v224
	v_add_f32_e32 v224, v113, v224
	s_waitcnt lgkmcnt(6)
	v_mfma_f32_32x32x16_bf16 v[18:33], v[98:101], v[134:137], v[18:33]
	ds_read_b64_tr_b16 v[146:147], v199 offset:15488
	ds_read_b64_tr_b16 v[148:149], v199 offset:18048
	v_exp_f32_e32 v66, v66
	v_exp_f32_e32 v67, v67
	v_add_f32_e32 v224, v66, v224
	v_add_f32_e32 v224, v67, v224
	s_waitcnt lgkmcnt(6)
	v_mfma_f32_32x32x16_bf16 v[2:17], v[204:207], v[134:137], v[2:17]
	ds_read_b64_tr_b16 v[98:99], v199 offset:15552
	ds_read_b64_tr_b16 v[100:101], v199 offset:18112
	v_exp_f32_e32 v68, v68
	v_cvt_pk_bf16_f32 v138, v106, v107
	v_add_f32_e32 v224, v68, v224
	v_cvt_pk_bf16_f32 v141, v112, v113
	s_waitcnt lgkmcnt(6)
	v_mfma_f32_32x32x16_bf16 v[50:65], v[208:211], v[130:133], v[50:65]
	ds_read_b128 v[200:203], v196
	v_exp_f32_e32 v69, v69
	v_exp_f32_e32 v70, v70
	v_add_f32_e32 v224, v69, v224
	v_add_f32_e32 v224, v70, v224
	s_waitcnt lgkmcnt(5)
	v_mfma_f32_32x32x16_bf16 v[34:49], v[102:105], v[130:133], v[34:49]
	ds_read_b128 v[204:207], v196 offset:8704
	v_exp_f32_e32 v71, v71
	v_cvt_pk_bf16_f32 v139, v108, v109
	v_add_f32_e32 v224, v71, v224
	v_cvt_pk_bf16_f32 v134, v66, v67
	v_cvt_pk_bf16_f32 v135, v68, v69
	s_waitcnt lgkmcnt(4)
	v_mfma_f32_32x32x16_bf16 v[18:33], v[146:149], v[130:133], v[18:33]
	ds_read_b128 v[208:211], v196 offset:32
	v_exp_f32_e32 v72, v72
	v_exp_f32_e32 v73, v73
	v_add_f32_e32 v224, v72, v224
	v_add_f32_e32 v224, v73, v224
	s_waitcnt lgkmcnt(3)
	v_mfma_f32_32x32x16_bf16 v[2:17], v[98:101], v[130:133], v[2:17]
	ds_read_b128 v[146:149], v196 offset:8736
	ds_read_b128 v[66:69], v196 offset:64
	v_exp_f32_e32 v74, v74
	v_exp_f32_e32 v75, v75
	v_add_f32_e32 v224, v74, v224
	v_add_f32_e32 v224, v75, v224
	s_waitcnt lgkmcnt(4)
	v_mfma_f32_32x32x16_bf16 v[98:113], v[200:203], v[114:117], v[228:243]
	v_exp_f32_e32 v76, v76
	v_cvt_pk_bf16_f32 v136, v70, v71
	v_add_f32_e32 v224, v76, v224
	s_waitcnt lgkmcnt(3)
	v_mfma_f32_32x32x16_bf16 v[82:97], v[204:207], v[114:117], v[228:243]
	ds_read_b128 v[200:203], v196 offset:8768
	v_exp_f32_e32 v77, v77
	v_exp_f32_e32 v78, v78
	v_add_f32_e32 v224, v77, v224
	v_add_f32_e32 v224, v78, v224
	s_waitcnt lgkmcnt(3)
	v_mfma_f32_32x32x16_bf16 v[98:113], v[208:211], v[118:121], v[98:113]
	ds_read_b128 v[204:207], v196 offset:96
	v_exp_f32_e32 v79, v79
	v_cvt_pk_bf16_f32 v137, v72, v73
	v_add_f32_e32 v224, v79, v224
	s_waitcnt lgkmcnt(3)
	v_mfma_f32_32x32x16_bf16 v[82:97], v[146:149], v[118:121], v[82:97]
	ds_read_b128 v[70:73], v196 offset:8800
	v_exp_f32_e32 v80, v80
	v_exp_f32_e32 v81, v81
	v_add_f32_e32 v224, v80, v224
	v_add_f32_e32 v224, v81, v224
	s_waitcnt lgkmcnt(3)
	v_mfma_f32_32x32x16_bf16 v[98:113], v[66:69], v[122:125], v[98:113]
	s_waitcnt vmcnt(3)
	ds_write_b128 v190, v[162:165] offset:25600
	s_waitcnt vmcnt(2)
	ds_write_b128 v188, v[158:161] offset:25600
	v_cvt_pk_bf16_f32 v130, v74, v75
	s_waitcnt lgkmcnt(4)
	v_mfma_f32_32x32x16_bf16 v[82:97], v[200:203], v[122:125], v[82:97]
	v_cvt_pk_bf16_f32 v131, v76, v77
	s_waitcnt lgkmcnt(3)
	v_mfma_f32_32x32x16_bf16 v[98:113], v[204:207], v[126:129], v[98:113]
	v_add_u32_e32 v68, s37, v176
	s_waitcnt vmcnt(1)
	ds_write_b128 v68, v[150:153] offset:51200
	v_add_u32_e32 v68, s37, v178
	s_waitcnt vmcnt(0)
	ds_write_b128 v68, v[154:157] offset:51200
	s_cmpk_lt_u32 s76, 0x7f
	s_cselect_b32 s84, 0x4d000, 0
	s_add_u32 s84, s84, s88
	s_add_u32 s84, s8, s84
	s_addc_u32 s85, s9, 0
	s_add_u32 s98, s8, s88
	s_addc_u32 s99, s9, 0
	v_cvt_pk_bf16_f32 v132, v78, v79
	s_waitcnt lgkmcnt(4)
	v_mfma_f32_32x32x16_bf16 v[82:97], v[70:73], v[126:129], v[82:97]
	v_cvt_pk_bf16_f32 v133, v80, v81
	v_mov_b32_e32 v199, v224
	s_mul_i32 s37, s77, 0x5000
	v_add_u32_e32 v201, s37, v192
	ds_read_b64_tr_b16 v[158:159], v201 offset:51200
	ds_read_b64_tr_b16 v[154:155], v201 offset:51264
	ds_read_b64_tr_b16 v[150:151], v201 offset:51328
	ds_read_b64_tr_b16 v[146:147], v201 offset:51392
	ds_read_b64_tr_b16 v[160:161], v201 offset:53760
	ds_read_b64_tr_b16 v[156:157], v201 offset:53824
	ds_read_b64_tr_b16 v[152:153], v201 offset:53888
	ds_read_b64_tr_b16 v[148:149], v201 offset:53952
	s_andn2_b64 vcc, exec, s[6:7]
	v_add_u32_e32 v200, s75, v179
	s_cbranch_vccnz .LBB0_987
	v_add_u32_e32 v66, 0x80, v200
	v_med3_i32 v67, v66, 0, v216
	v_med3_i32 v66, v66, s46, v217
	v_lshl_add_u32 v68, v66, 2, s15
	v_add_u32_e32 v66, 0x81, v200
	v_med3_i32 v69, v66, 0, v216
	v_med3_i32 v66, v66, s46, v217
	v_lshl_add_u32 v70, v66, 2, s15
	v_add_u32_e32 v66, 0x82, v200
	v_med3_i32 v71, v66, 0, v216
	v_med3_i32 v66, v66, s46, v217
	v_lshl_add_u32 v72, v66, 2, s15
	v_add_u32_e32 v66, 0x83, v200
	v_med3_i32 v73, v66, 0, v216
	v_med3_i32 v66, v66, s46, v217
	v_lshl_add_u32 v67, v67, 2, s15
	v_lshl_add_u32 v69, v69, 2, s15
	v_lshl_add_u32 v71, v71, 2, s15
	v_lshl_add_u32 v73, v73, 2, s15
	v_lshl_add_u32 v74, v66, 2, s15
	ds_read_b32 v66, v67
	ds_read_b32 v68, v68 offset:128
	ds_read_b32 v67, v69
	ds_read_b32 v69, v70 offset:128
	ds_read_b32 v70, v71
	ds_read_b32 v72, v72 offset:128
	ds_read_b32 v71, v73
	ds_read_b32 v73, v74 offset:128
	v_add_u32_e32 v74, 0x88, v200
	v_med3_i32 v75, v74, 0, v216
	v_med3_i32 v74, v74, s46, v217
	v_lshl_add_u32 v76, v74, 2, s15
	v_add_u32_e32 v74, 0x89, v200
	v_med3_i32 v77, v74, 0, v216
	v_med3_i32 v74, v74, s46, v217
	v_lshl_add_u32 v78, v74, 2, s15
	v_add_u32_e32 v74, 0x8a, v200
	v_med3_i32 v79, v74, 0, v216
	v_med3_i32 v74, v74, s46, v217
	v_lshl_add_u32 v80, v74, 2, s15
	v_add_u32_e32 v74, 0x8b, v200
	v_med3_i32 v81, v74, 0, v216
	v_med3_i32 v74, v74, s46, v217
	v_lshl_add_u32 v75, v75, 2, s15
	v_lshl_add_u32 v77, v77, 2, s15
	v_lshl_add_u32 v79, v79, 2, s15
	v_lshl_add_u32 v81, v81, 2, s15
	v_lshl_add_u32 v162, v74, 2, s15
	ds_read_b32 v74, v75
	ds_read_b32 v76, v76 offset:128
	ds_read_b32 v75, v77
	ds_read_b32 v77, v78 offset:128
	ds_read_b32 v78, v79
	ds_read_b32 v80, v80 offset:128
	ds_read_b32 v79, v81
	ds_read_b32 v81, v162 offset:128
	v_add_u32_e32 v162, 0x90, v200
	v_med3_i32 v163, v162, 0, v216
	v_med3_i32 v162, v162, s46, v217
	v_lshl_add_u32 v164, v162, 2, s15
	v_add_u32_e32 v162, 0x91, v200
	v_med3_i32 v165, v162, 0, v216
	v_med3_i32 v162, v162, s46, v217
	v_lshl_add_u32 v180, v162, 2, s15
	v_add_u32_e32 v162, 0x92, v200
	v_med3_i32 v202, v162, 0, v216
	v_med3_i32 v162, v162, s46, v217
	v_add_u32_e32 v207, 0x99, v200
	v_lshl_add_u32 v203, v162, 2, s15
	v_add_u32_e32 v162, 0x93, v200
	v_med3_i32 v208, v207, 0, v216
	v_med3_i32 v207, v207, s46, v217
	v_med3_i32 v204, v162, 0, v216
	v_lshl_add_u32 v214, v207, 2, s15
	v_add_u32_e32 v207, 0x9a, v200
	v_lshl_add_u32 v163, v163, 2, s15
	v_lshl_add_u32 v165, v165, 2, s15
	v_lshl_add_u32 v202, v202, 2, s15
	v_med3_i32 v162, v162, s46, v217
	v_lshl_add_u32 v205, v204, 2, s15
	v_lshl_add_u32 v209, v208, 2, s15
	v_med3_i32 v208, v207, 0, v216
	v_med3_i32 v207, v207, s46, v217
	v_lshl_add_u32 v206, v162, 2, s15
	ds_read_b32 v162, v163
	ds_read_b32 v164, v164 offset:128
	ds_read_b32 v163, v165
	ds_read_b32 v165, v180 offset:128
	ds_read_b32 v202, v202
	ds_read_b32 v204, v203 offset:128
	ds_read_b32 v203, v205
	ds_read_b32 v205, v206 offset:128
	v_add_u32_e32 v180, 0x98, v200
	v_lshl_add_u32 v212, v207, 2, s15
	v_add_u32_e32 v207, 0x9b, v200
	v_med3_i32 v206, v180, 0, v216
	v_lshl_add_u32 v210, v208, 2, s15
	v_med3_i32 v208, v207, 0, v216
	v_med3_i32 v207, v207, s46, v217
	v_med3_i32 v180, v180, s46, v217
	v_lshl_add_u32 v206, v206, 2, s15
	v_lshl_add_u32 v211, v208, 2, s15
	v_lshl_add_u32 v213, v207, 2, s15
	v_lshl_add_u32 v180, v180, 2, s15
	ds_read_b32 v206, v206
	ds_read_b32 v208, v180 offset:128
	ds_read_b32 v210, v210
	ds_read_b32 v211, v211
	ds_read_b32 v207, v209
	ds_read_b32 v213, v213 offset:128
	ds_read_b32 v212, v212 offset:128
	ds_read_b32 v209, v214 offset:128
	s_waitcnt lgkmcnt(4)
	v_pk_add_f32 v[112:113], v[112:113], v[210:211]
	s_waitcnt lgkmcnt(3)
	v_pk_add_f32 v[110:111], v[110:111], v[206:207]
	v_pk_add_f32 v[108:109], v[108:109], v[202:203]
	v_pk_add_f32 v[106:107], v[106:107], v[162:163]
	v_pk_add_f32 v[104:105], v[104:105], v[78:79]
	v_pk_add_f32 v[102:103], v[102:103], v[74:75]
	v_pk_add_f32 v[100:101], v[100:101], v[70:71]
	v_pk_add_f32 v[98:99], v[98:99], v[66:67]
	s_waitcnt lgkmcnt(1)
	v_pk_add_f32 v[96:97], v[96:97], v[212:213]
	s_waitcnt lgkmcnt(0)
	v_pk_add_f32 v[94:95], v[94:95], v[208:209]
	v_pk_add_f32 v[92:93], v[92:93], v[204:205]
	v_pk_add_f32 v[90:91], v[90:91], v[164:165]
	v_pk_add_f32 v[88:89], v[88:89], v[80:81]
	v_pk_add_f32 v[86:87], v[86:87], v[76:77]
	v_pk_add_f32 v[84:85], v[84:85], v[72:73]
	v_pk_add_f32 v[82:83], v[82:83], v[68:69]

.LBB0_992:
	v_mfma_f32_32x32x16_bf16 v[50:65], v[158:161], v[142:145], v[50:65]
	s_cmpk_lt_i32 s36, 0x5b
	s_cselect_b64 s[36:37], -1, 0
	s_add_i32 s6, s75, 0xffffff40
	s_addk_i32 s52, 0xff40
	s_cmpk_lt_i32 s52, 0xfea7
	s_cselect_b64 s[4:5], -1, 0
	s_cmp_gt_i32 s6, s71
	s_cselect_b64 s[6:7], -1, 0
	v_add_u32_e32 v210, 0xc800, v201
	s_cmpk_gt_u32 s76, 0x7e
	s_cselect_b64 s[52:53], -1, 0
	ds_read_b64_tr_b16 v[202:203], v201 offset:56320
	ds_read_b64_tr_b16 v[204:205], v201 offset:58880
	s_mul_i32 s79, s74, 0x5000
	s_add_i32 s79, s79, 0
	v_mov_b32_e32 v224, 0
	v_exp_f32_e32 v98, v98
	v_exp_f32_e32 v99, v99
	v_add_f32_e32 v224, v98, v224
	v_add_f32_e32 v224, v99, v224
	v_mfma_f32_32x32x16_bf16 v[34:49], v[154:157], v[142:145], v[34:49]
	ds_read_b64_tr_b16 v[206:207], v201 offset:56384
	ds_read_b64_tr_b16 v[208:209], v201 offset:58944
	ds_read_b64_tr_b16 v[220:221], v201 offset:56448
	ds_read_b64_tr_b16 v[222:223], v201 offset:59008
	global_load_dwordx4 v[162:165], v168, s[84:85] offset:1024
	global_load_dwordx4 v[158:161], v170, s[84:85] offset:1024
	v_exp_f32_e32 v100, v100
	v_mfma_f32_32x32x16_bf16 v[18:33], v[150:153], v[142:145], v[18:33]
	global_load_dwordx4 v[150:153], v168, s[98:99] offset:2048
	global_load_dwordx4 v[154:157], v170, s[98:99] offset:2048
	v_add_f32_e32 v224, v100, v224
	v_exp_f32_e32 v101, v101
	v_exp_f32_e32 v102, v102
	v_add_f32_e32 v224, v101, v224
	v_add_f32_e32 v224, v102, v224
	v_mfma_f32_32x32x16_bf16 v[2:17], v[146:149], v[142:145], v[2:17]
	ds_read_b64_tr_b16 v[182:183], v201 offset:56512
	ds_read_b64_tr_b16 v[184:185], v201 offset:59072
	v_exp_f32_e32 v103, v103
	s_waitcnt lgkmcnt(6)
	v_mfma_f32_32x32x16_bf16 v[50:65], v[202:205], v[138:141], v[50:65]
	ds_read_b64_tr_b16 v[146:147], v201 offset:61440
	ds_read_b64_tr_b16 v[148:149], v201 offset:64000
	v_add_f32_e32 v224, v103, v224
	v_exp_f32_e32 v104, v104
	v_exp_f32_e32 v105, v105
	v_add_f32_e32 v224, v104, v224
	v_add_f32_e32 v224, v105, v224
	v_cvt_pk_bf16_f32 v142, v98, v99
	s_waitcnt lgkmcnt(6)
	v_mfma_f32_32x32x16_bf16 v[34:49], v[206:209], v[138:141], v[34:49]
	ds_read_b64_tr_b16 v[202:203], v201 offset:61504
	ds_read_b64_tr_b16 v[204:205], v201 offset:64064
	v_exp_f32_e32 v106, v106
	v_exp_f32_e32 v107, v107
	v_add_f32_e32 v224, v106, v224
	v_add_f32_e32 v224, v107, v224
	v_cvt_pk_bf16_f32 v143, v100, v101
	s_waitcnt lgkmcnt(6)
	v_mfma_f32_32x32x16_bf16 v[18:33], v[220:223], v[138:141], v[18:33]
	ds_read_b64_tr_b16 v[98:99], v201 offset:61568
	ds_read_b64_tr_b16 v[100:101], v201 offset:64128
	v_exp_f32_e32 v108, v108
	v_cvt_pk_bf16_f32 v144, v102, v103
	v_add_f32_e32 v224, v108, v224
	s_waitcnt lgkmcnt(6)
	v_mfma_f32_32x32x16_bf16 v[2:17], v[182:185], v[138:141], v[2:17]
	ds_read_b64_tr_b16 v[206:207], v201 offset:61632
	ds_read_b64_tr_b16 v[208:209], v201 offset:64192
	v_exp_f32_e32 v109, v109
	v_exp_f32_e32 v110, v110
	v_add_f32_e32 v224, v109, v224
	v_add_f32_e32 v224, v110, v224
	s_waitcnt lgkmcnt(6)
	v_mfma_f32_32x32x16_bf16 v[50:65], v[146:149], v[134:137], v[50:65]
	ds_read_b64_tr_b16 v[182:183], v210 offset:15360
	ds_read_b64_tr_b16 v[184:185], v210 offset:17920
	v_exp_f32_e32 v111, v111
	v_cvt_pk_bf16_f32 v145, v104, v105
	v_add_f32_e32 v224, v111, v224
	v_cvt_pk_bf16_f32 v140, v110, v111
	s_waitcnt lgkmcnt(6)
	v_mfma_f32_32x32x16_bf16 v[34:49], v[202:205], v[134:137], v[34:49]
	ds_read_b64_tr_b16 v[102:103], v210 offset:15424
	ds_read_b64_tr_b16 v[104:105], v210 offset:17984
	v_exp_f32_e32 v112, v112
	v_exp_f32_e32 v113, v113
	v_add_f32_e32 v224, v112, v224
	v_add_f32_e32 v224, v113, v224
	s_waitcnt lgkmcnt(6)
	v_mfma_f32_32x32x16_bf16 v[18:33], v[98:101], v[134:137], v[18:33]
	ds_read_b64_tr_b16 v[146:147], v210 offset:15488
	ds_read_b64_tr_b16 v[148:149], v210 offset:18048
	v_exp_f32_e32 v82, v82
	v_exp_f32_e32 v83, v83
	v_add_f32_e32 v224, v82, v224
	v_add_f32_e32 v224, v83, v224
	s_waitcnt lgkmcnt(6)
	v_mfma_f32_32x32x16_bf16 v[2:17], v[206:209], v[134:137], v[2:17]
	ds_read_b64_tr_b16 v[98:99], v210 offset:15552
	ds_read_b64_tr_b16 v[100:101], v210 offset:18112
	v_exp_f32_e32 v84, v84
	v_cvt_pk_bf16_f32 v138, v106, v107
	v_add_f32_e32 v224, v84, v224
	v_cvt_pk_bf16_f32 v141, v112, v113
	s_waitcnt lgkmcnt(6)
	v_mfma_f32_32x32x16_bf16 v[50:65], v[182:185], v[130:133], v[50:65]
	ds_read_b128 v[202:205], v196 offset:25600
	v_exp_f32_e32 v85, v85
	v_exp_f32_e32 v86, v86
	v_add_f32_e32 v224, v85, v224
	v_add_f32_e32 v224, v86, v224
	s_waitcnt lgkmcnt(5)
	v_mfma_f32_32x32x16_bf16 v[34:49], v[102:105], v[130:133], v[34:49]
	ds_read_b128 v[182:185], v196 offset:34304
	v_exp_f32_e32 v87, v87
	v_cvt_pk_bf16_f32 v139, v108, v109
	v_add_f32_e32 v224, v87, v224
	v_cvt_pk_bf16_f32 v134, v82, v83
	v_cvt_pk_bf16_f32 v135, v84, v85
	s_waitcnt lgkmcnt(4)
	v_mfma_f32_32x32x16_bf16 v[18:33], v[146:149], v[130:133], v[18:33]
	ds_read_b128 v[206:209], v196 offset:25632
	v_exp_f32_e32 v88, v88
	v_exp_f32_e32 v89, v89
	v_add_f32_e32 v224, v88, v224
	v_add_f32_e32 v224, v89, v224
	s_waitcnt lgkmcnt(3)
	v_mfma_f32_32x32x16_bf16 v[2:17], v[98:101], v[130:133], v[2:17]
	ds_read_b128 v[146:149], v196 offset:34336
	ds_read_b128 v[82:85], v196 offset:25664
	v_exp_f32_e32 v90, v90
	v_exp_f32_e32 v91, v91
	v_add_f32_e32 v224, v90, v224
	v_add_f32_e32 v224, v91, v224
	s_waitcnt lgkmcnt(4)
	v_mfma_f32_32x32x16_bf16 v[98:113], v[202:205], v[114:117], v[228:243]
	v_exp_f32_e32 v92, v92
	v_cvt_pk_bf16_f32 v136, v86, v87
	v_add_f32_e32 v224, v92, v224
	s_waitcnt lgkmcnt(3)
	v_mfma_f32_32x32x16_bf16 v[66:81], v[182:185], v[114:117], v[228:243]
	ds_read_b128 v[202:205], v196 offset:34368
	v_exp_f32_e32 v93, v93
	v_exp_f32_e32 v94, v94
	v_add_f32_e32 v224, v93, v224
	v_add_f32_e32 v224, v94, v224
	s_waitcnt lgkmcnt(3)
	v_mfma_f32_32x32x16_bf16 v[98:113], v[206:209], v[118:121], v[98:113]
	ds_read_b128 v[182:185], v196 offset:25696
	v_exp_f32_e32 v95, v95
	v_cvt_pk_bf16_f32 v137, v88, v89
	v_add_f32_e32 v224, v95, v224
	s_waitcnt lgkmcnt(3)
	v_mfma_f32_32x32x16_bf16 v[66:81], v[146:149], v[118:121], v[66:81]
	ds_read_b128 v[86:89], v196 offset:34400
	v_exp_f32_e32 v96, v96
	v_exp_f32_e32 v97, v97
	v_add_f32_e32 v224, v96, v224
	v_add_f32_e32 v224, v97, v224
	s_waitcnt lgkmcnt(3)
	v_mfma_f32_32x32x16_bf16 v[98:113], v[82:85], v[122:125], v[98:113]
	s_waitcnt vmcnt(3)
	ds_write_b128 v190, v[162:165]
	s_waitcnt vmcnt(2)
	ds_write_b128 v188, v[158:161]
	v_cvt_pk_bf16_f32 v130, v90, v91
	s_waitcnt lgkmcnt(4)
	v_mfma_f32_32x32x16_bf16 v[66:81], v[202:205], v[122:125], v[66:81]
	v_cvt_pk_bf16_f32 v131, v92, v93
	s_waitcnt lgkmcnt(3)
	v_mfma_f32_32x32x16_bf16 v[98:113], v[182:185], v[126:129], v[98:113]
	v_add_u32_e32 v84, s79, v176
	s_waitcnt vmcnt(1)
	ds_write_b128 v84, v[150:153] offset:51200
	v_add_u32_e32 v84, s79, v178
	s_waitcnt vmcnt(0)
	ds_write_b128 v84, v[154:157] offset:51200
	s_cmpk_lt_u32 s76, 0x7f
	s_cselect_b32 s84, s67, 0
	s_cselect_b32 s98, 0x4d000, 0
	s_add_u32 s84, s84, s88
	s_add_u32 s98, s98, s88
	s_add_u32 s84, s8, s84
	s_addc_u32 s85, s9, 0
	s_add_u32 s98, s8, s98
	s_addc_u32 s99, s9, 0
	v_cvt_pk_bf16_f32 v132, v94, v95
	s_waitcnt lgkmcnt(4)
	v_mfma_f32_32x32x16_bf16 v[66:81], v[86:89], v[126:129], v[66:81]
	v_cvt_pk_bf16_f32 v133, v96, v97
	v_mov_b32_e32 v163, v224
	v_add_u32_e32 v82, s78, v192
	ds_read_b64_tr_b16 v[158:159], v82 offset:51200
	ds_read_b64_tr_b16 v[154:155], v82 offset:51264
	ds_read_b64_tr_b16 v[150:151], v82 offset:51328
	ds_read_b64_tr_b16 v[146:147], v82 offset:51392
	ds_read_b64_tr_b16 v[160:161], v82 offset:53760
	ds_read_b64_tr_b16 v[156:157], v82 offset:53824
	ds_read_b64_tr_b16 v[152:153], v82 offset:53888
	ds_read_b64_tr_b16 v[148:149], v82 offset:53952
	s_and_b64 s[0:1], s[0:1], s[36:37]
	s_andn2_b64 vcc, exec, s[0:1]
	s_cbranch_vccnz .LBB0_994
	v_add_u32_e32 v82, 0xc0, v200
	v_med3_i32 v83, v82, 0, v216
	v_med3_i32 v82, v82, s46, v217
	v_lshl_add_u32 v84, v82, 2, s15
	v_add_u32_e32 v82, 0xc1, v200
	v_med3_i32 v85, v82, 0, v216
	v_med3_i32 v82, v82, s46, v217
	v_lshl_add_u32 v86, v82, 2, s15
	v_add_u32_e32 v82, 0xc2, v200
	v_med3_i32 v87, v82, 0, v216
	v_med3_i32 v82, v82, s46, v217
	v_lshl_add_u32 v88, v82, 2, s15
	v_add_u32_e32 v82, 0xc3, v200
	v_med3_i32 v89, v82, 0, v216
	v_med3_i32 v82, v82, s46, v217
	v_lshl_add_u32 v83, v83, 2, s15
	v_lshl_add_u32 v85, v85, 2, s15
	v_lshl_add_u32 v87, v87, 2, s15
	v_lshl_add_u32 v89, v89, 2, s15
	v_lshl_add_u32 v90, v82, 2, s15
	ds_read_b32 v82, v83
	ds_read_b32 v84, v84 offset:128
	ds_read_b32 v83, v85
	ds_read_b32 v85, v86 offset:128
	ds_read_b32 v86, v87
	ds_read_b32 v88, v88 offset:128
	ds_read_b32 v87, v89
	ds_read_b32 v89, v90 offset:128
	v_add_u32_e32 v90, 0xc8, v200
	v_med3_i32 v91, v90, 0, v216
	v_med3_i32 v90, v90, s46, v217
	v_lshl_add_u32 v92, v90, 2, s15
	v_add_u32_e32 v90, 0xc9, v200
	v_med3_i32 v93, v90, 0, v216
	v_med3_i32 v90, v90, s46, v217
	v_lshl_add_u32 v94, v90, 2, s15
	v_add_u32_e32 v90, 0xca, v200
	v_med3_i32 v95, v90, 0, v216
	v_med3_i32 v90, v90, s46, v217
	v_add_u32_e32 v165, 0xd1, v200
	v_lshl_add_u32 v96, v90, 2, s15
	v_add_u32_e32 v90, 0xcb, v200
	v_med3_i32 v182, v165, 0, v216
	v_med3_i32 v165, v165, s46, v217
	v_med3_i32 v97, v90, 0, v216
	v_med3_i32 v90, v90, s46, v217
	v_lshl_add_u32 v184, v165, 2, s15
	v_add_u32_e32 v165, 0xd2, v200
	v_lshl_add_u32 v91, v91, 2, s15
	v_lshl_add_u32 v93, v93, 2, s15
	v_lshl_add_u32 v95, v95, 2, s15
	v_lshl_add_u32 v97, v97, 2, s15
	v_lshl_add_u32 v162, v90, 2, s15
	v_lshl_add_u32 v183, v182, 2, s15
	v_med3_i32 v182, v165, 0, v216
	v_med3_i32 v165, v165, s46, v217
	ds_read_b32 v90, v91
	ds_read_b32 v92, v92 offset:128
	ds_read_b32 v91, v93
	ds_read_b32 v93, v94 offset:128
	ds_read_b32 v94, v95
	ds_read_b32 v96, v96 offset:128
	ds_read_b32 v95, v97
	ds_read_b32 v97, v162 offset:128
	v_add_u32_e32 v162, 0xd0, v200
	v_lshl_add_u32 v201, v165, 2, s15
	v_add_u32_e32 v165, 0xd3, v200
	v_med3_i32 v164, v162, 0, v216
	v_lshl_add_u32 v185, v182, 2, s15
	v_med3_i32 v182, v165, 0, v216
	v_med3_i32 v165, v165, s46, v217
	v_med3_i32 v162, v162, s46, v217
	v_lshl_add_u32 v164, v164, 2, s15
	v_lshl_add_u32 v203, v182, 2, s15
	v_lshl_add_u32 v204, v165, 2, s15
	v_lshl_add_u32 v162, v162, 2, s15
	ds_read_b32 v164, v164
	ds_read_b32 v182, v162 offset:128
	ds_read_b32 v165, v183
	ds_read_b32 v183, v184 offset:128
	ds_read_b32 v184, v185
	ds_read_b32 v202, v201 offset:128
	ds_read_b32 v185, v203
	ds_read_b32 v203, v204 offset:128
	v_add_u32_e32 v204, 0xd9, v200
	v_med3_i32 v205, v204, 0, v216
	v_med3_i32 v204, v204, s46, v217
	v_lshl_add_u32 v210, v204, 2, s15
	v_add_u32_e32 v204, 0xda, v200
	v_add_u32_e32 v162, 0xd8, v200
	v_med3_i32 v206, v204, 0, v216
	v_med3_i32 v204, v204, s46, v217
	v_add_u32_e32 v200, 0xdb, v200
	v_med3_i32 v201, v162, 0, v216
	v_lshl_add_u32 v208, v204, 2, s15
	v_med3_i32 v204, v200, 0, v216
	v_med3_i32 v200, v200, s46, v217
	v_med3_i32 v162, v162, s46, v217
	v_lshl_add_u32 v201, v201, 2, s15
	v_lshl_add_u32 v205, v205, 2, s15
	v_lshl_add_u32 v206, v206, 2, s15
	v_lshl_add_u32 v207, v204, 2, s15
	v_lshl_add_u32 v209, v200, 2, s15
	v_lshl_add_u32 v162, v162, 2, s15
	ds_read_b32 v200, v201
	ds_read_b32 v204, v162 offset:128
	ds_read_b32 v206, v206
	ds_read_b32 v207, v207
	ds_read_b32 v201, v205
	ds_read_b32 v209, v209 offset:128
	ds_read_b32 v208, v208 offset:128
	ds_read_b32 v205, v210 offset:128
	s_waitcnt lgkmcnt(4)
	v_pk_add_f32 v[112:113], v[112:113], v[206:207]
	s_waitcnt lgkmcnt(3)
	v_pk_add_f32 v[110:111], v[110:111], v[200:201]
	v_pk_add_f32 v[108:109], v[108:109], v[184:185]
	v_pk_add_f32 v[106:107], v[106:107], v[164:165]
	v_pk_add_f32 v[104:105], v[104:105], v[94:95]
	v_pk_add_f32 v[102:103], v[102:103], v[90:91]
	v_pk_add_f32 v[100:101], v[100:101], v[86:87]
	v_pk_add_f32 v[98:99], v[98:99], v[82:83]
	s_waitcnt lgkmcnt(1)
	v_pk_add_f32 v[80:81], v[80:81], v[208:209]
	s_waitcnt lgkmcnt(0)
	v_pk_add_f32 v[78:79], v[78:79], v[204:205]
	v_pk_add_f32 v[76:77], v[76:77], v[202:203]
	v_pk_add_f32 v[74:75], v[74:75], v[182:183]
	v_pk_add_f32 v[72:73], v[72:73], v[96:97]
	v_pk_add_f32 v[70:71], v[70:71], v[92:93]
	v_pk_add_f32 v[68:69], v[68:69], v[88:89]
	v_pk_add_f32 v[66:67], v[66:67], v[84:85]
